# grid barrier in-loop copies: non-leaders poll the cross-XCD release word directly, no XGEN re-publication, agent-scope L1 invalidate issued early (behind the arrival) instead of after the release; on
# speedup vs baseline: 1.0116x; 1.0116x over previous
; __device__ __forceinline__ unsigned xb_ld(unsigned* p)              { return __hip_atomic_load(p, __ATOMIC_RELAXED, __HIP_MEMORY_SCOPE_AGENT); }
; __device__ __forceinline__ unsigned xb_add(unsigned* p, unsigned v) { return __hip_atomic_fetch_add(p, v, __ATOMIC_RELAXED, __HIP_MEMORY_SCOPE_AGENT); }
; #define XB_SPIN(cond, bar) do { unsigned _sp = 0; while (cond) { __builtin_amdgcn_s_sleep(1); \
;     if ((++_sp & 255u) == 0u) { if (xb_ld(&(bar)[XB_TMO])) break; if (_sp > XB_SPIN_CAP) { atomicAdd(&(bar)[XB_TMO], 1u); break; } } } } while (0)
; __device__ __forceinline__ void xcd_barrier(const XcdBarrier& b) {
;     ...
;             if (og + 1u == (tg + 1u) * nx) xb_add(&bar[XB_TOPGEN], 1u);
;             else XB_SPIN(xb_ld(&bar[XB_TOPGEN]) == tg, bar);
;             __builtin_amdgcn_fence(__ATOMIC_ACQUIRE, "agent");
;             xb_add(&bar[XB_XGEN(b.x)], 1u);
;             asm volatile("s_waitcnt vmcnt(0)" ::: "memory");
.LBB0_167:
	s_or_b64 exec, exec, s[16:17]
	s_waitcnt vmcnt(0)
	s_waitcnt vmcnt(0)

; __device__ __forceinline__ unsigned xb_ld(unsigned* p)              { return __hip_atomic_load(p, __ATOMIC_RELAXED, __HIP_MEMORY_SCOPE_AGENT); }
; __device__ __forceinline__ unsigned xb_add(unsigned* p, unsigned v) { return __hip_atomic_fetch_add(p, v, __ATOMIC_RELAXED, __HIP_MEMORY_SCOPE_AGENT); }
; #define XB_SPIN(cond, bar) do { unsigned _sp = 0; while (cond) { __builtin_amdgcn_s_sleep(1); \
;     if ((++_sp & 255u) == 0u) { if (xb_ld(&(bar)[XB_TMO])) break; if (_sp > XB_SPIN_CAP) { atomicAdd(&(bar)[XB_TMO], 1u); break; } } } } while (0)
; __device__ __forceinline__ void xcd_barrier(const XcdBarrier& b) {
;     ...
;         const unsigned old = xb_add(&bar[XB_XSUB(b.x)], 1u);
;         const unsigned gen = old / nloc;
;         if (old + 1u == (gen + 1u) * nloc) {
;             __builtin_amdgcn_fence(__ATOMIC_RELEASE, "agent");
;             asm volatile("s_waitcnt vmcnt(0)" ::: "memory");
;             const unsigned og = xb_add(&bar[XB_TOP], 1u);
;             const unsigned tg = og / nx;
;             if (og + 1u == (tg + 1u) * nx) xb_add(&bar[XB_TOPGEN], 1u);
;             else XB_SPIN(xb_ld(&bar[XB_TOPGEN]) == tg, bar);
;             __builtin_amdgcn_fence(__ATOMIC_ACQUIRE, "agent");
;             xb_add(&bar[XB_XGEN(b.x)], 1u);
;             asm volatile("s_waitcnt vmcnt(0)" ::: "memory");
;         } else {
;             XB_SPIN(xb_ld(&bar[XB_XGEN(b.x)]) == gen, bar);
;             __builtin_amdgcn_fence(__ATOMIC_ACQUIRE, "agent");
.LBB0_190:
	global_atomic_add v4, v[190:191], v220, off sc0
	v_cvt_f32_u32_e32 v2, v3
	v_sub_u32_e32 v5, 0, v3
	v_rcp_iflag_f32_e32 v2, v2
	s_nop 0
	v_mul_f32_e32 v2, 0x4f7ffffe, v2
	v_cvt_u32_f32_e32 v2, v2
	v_mul_lo_u32 v5, v5, v2
	v_mul_hi_u32 v5, v2, v5
	v_add_u32_e32 v2, v2, v5
	s_waitcnt vmcnt(0)
	v_mul_hi_u32 v2, v4, v2
	v_mul_lo_u32 v5, v2, v3
	v_sub_u32_e32 v5, v4, v5
	v_add_u32_e32 v6, 1, v2
	v_sub_u32_e32 v7, v5, v3
	v_cmp_ge_u32_e32 vcc, v5, v3
	v_add_u32_e32 v4, 1, v4
	s_nop 0
	v_cndmask_b32_e32 v2, v2, v6, vcc
	v_cndmask_b32_e32 v5, v5, v7, vcc
	v_add_u32_e32 v6, 1, v2
	v_cmp_ge_u32_e32 vcc, v5, v3
	s_nop 1
	v_cndmask_b32_e32 v2, v2, v6, vcc
	v_mul_lo_u32 v5, v3, v2
	v_add_u32_e32 v3, v5, v3
	v_cmp_ne_u32_e32 vcc, v4, v3
	s_and_saveexec_b64 s[2:3], vcc
	s_xor_b64 s[16:17], exec, s[2:3]
	s_cbranch_execz .LBB0_204
	s_waitcnt lgkmcnt(0)
	buffer_inv sc1
	v_readlane_b32 s98, v247, 3
	v_readlane_b32 s99, v247, 4
	s_nop 4
	global_load_dword v0, v1, s[98:99] sc1
	s_waitcnt vmcnt(0)
	v_cmp_eq_u32_e32 vcc, v0, v2
	s_and_saveexec_b64 s[34:35], vcc
	s_cbranch_execz .LBB0_203
	s_mov_b32 s2, 1
	s_mov_b64 s[40:41], 0
	s_branch .LBB0_194

; __device__ __forceinline__ unsigned xb_ld(unsigned* p)              { return __hip_atomic_load(p, __ATOMIC_RELAXED, __HIP_MEMORY_SCOPE_AGENT); }
; __device__ __forceinline__ unsigned xb_add(unsigned* p, unsigned v) { return __hip_atomic_fetch_add(p, v, __ATOMIC_RELAXED, __HIP_MEMORY_SCOPE_AGENT); }
; #define XB_SPIN(cond, bar) do { unsigned _sp = 0; while (cond) { __builtin_amdgcn_s_sleep(1); \
;     if ((++_sp & 255u) == 0u) { if (xb_ld(&(bar)[XB_TMO])) break; if (_sp > XB_SPIN_CAP) { atomicAdd(&(bar)[XB_TMO], 1u); break; } } } } while (0)
; __device__ __forceinline__ void xcd_barrier(const XcdBarrier& b) {
;     ...
;         if (old + 1u == (gen + 1u) * nloc) {
;             __builtin_amdgcn_fence(__ATOMIC_RELEASE, "agent");
;             asm volatile("s_waitcnt vmcnt(0)" ::: "memory");
;             const unsigned og = xb_add(&bar[XB_TOP], 1u);
;     ...
;         } else {
;             XB_SPIN(xb_ld(&bar[XB_XGEN(b.x)]) == gen, bar);
;             __builtin_amdgcn_fence(__ATOMIC_ACQUIRE, "agent");
;             asm volatile("s_waitcnt vmcnt(0)" ::: "memory");
.LBB0_203:
	s_or_b64 exec, exec, s[34:35]
	s_waitcnt vmcnt(0)
	s_waitcnt vmcnt(0)
.LBB0_204:
	s_andn2_saveexec_b64 s[16:17], s[16:17]
	s_cbranch_execz .LBB0_222
	s_mov_b64 s[34:35], exec
	buffer_wbl2 sc1
	s_waitcnt lgkmcnt(0)
	s_waitcnt vmcnt(0)
	v_mbcnt_lo_u32_b32 v2, s34, 0
	v_mbcnt_hi_u32_b32 v2, s35, v2
	v_cmp_eq_u32_e32 vcc, 0, v2
	s_and_saveexec_b64 s[40:41], vcc
	s_cbranch_execz .LBB0_207
	s_bcnt1_i32_b64 s2, s[34:35]
	v_mov_b32_e32 v3, s2
	v_readlane_b32 s2, v247, 1
	v_readlane_b32 s3, v247, 2
	s_nop 4
	global_atomic_add v3, v1, v3, s[2:3] sc0
	buffer_inv sc1

; __device__ __forceinline__ unsigned xb_ld(unsigned* p)              { return __hip_atomic_load(p, __ATOMIC_RELAXED, __HIP_MEMORY_SCOPE_AGENT); }
; __device__ __forceinline__ unsigned xb_add(unsigned* p, unsigned v) { return __hip_atomic_fetch_add(p, v, __ATOMIC_RELAXED, __HIP_MEMORY_SCOPE_AGENT); }
; #define XB_SPIN(cond, bar) do { unsigned _sp = 0; while (cond) { __builtin_amdgcn_s_sleep(1); \
;     if ((++_sp & 255u) == 0u) { if (xb_ld(&(bar)[XB_TMO])) break; if (_sp > XB_SPIN_CAP) { atomicAdd(&(bar)[XB_TMO], 1u); break; } } } } while (0)
; __device__ __forceinline__ void xcd_barrier(const XcdBarrier& b) {
;     ...
;         const unsigned old = xb_add(&bar[XB_XSUB(b.x)], 1u);
;         const unsigned gen = old / nloc;
;         if (old + 1u == (gen + 1u) * nloc) {
;             __builtin_amdgcn_fence(__ATOMIC_RELEASE, "agent");
;             asm volatile("s_waitcnt vmcnt(0)" ::: "memory");
;             const unsigned og = xb_add(&bar[XB_TOP], 1u);
;             const unsigned tg = og / nx;
;             if (og + 1u == (tg + 1u) * nx) xb_add(&bar[XB_TOPGEN], 1u);
;             else XB_SPIN(xb_ld(&bar[XB_TOPGEN]) == tg, bar);
;             __builtin_amdgcn_fence(__ATOMIC_ACQUIRE, "agent");
;             xb_add(&bar[XB_XGEN(b.x)], 1u);
;             asm volatile("s_waitcnt vmcnt(0)" ::: "memory");
;         } else {
;             XB_SPIN(xb_ld(&bar[XB_XGEN(b.x)]) == gen, bar);
;             __builtin_amdgcn_fence(__ATOMIC_ACQUIRE, "agent");
.LBB0_295:
	global_atomic_add v4, v[190:191], v220, off sc0
	v_cvt_f32_u32_e32 v2, v3
	v_sub_u32_e32 v5, 0, v3
	v_rcp_iflag_f32_e32 v2, v2
	s_nop 0
	v_mul_f32_e32 v2, 0x4f7ffffe, v2
	v_cvt_u32_f32_e32 v2, v2
	v_mul_lo_u32 v5, v5, v2
	v_mul_hi_u32 v5, v2, v5
	v_add_u32_e32 v2, v2, v5
	s_waitcnt vmcnt(0)
	v_mul_hi_u32 v2, v4, v2
	v_mul_lo_u32 v5, v2, v3
	v_sub_u32_e32 v5, v4, v5
	v_add_u32_e32 v6, 1, v2
	v_sub_u32_e32 v7, v5, v3
	v_cmp_ge_u32_e32 vcc, v5, v3
	v_add_u32_e32 v4, 1, v4
	s_nop 0
	v_cndmask_b32_e32 v2, v2, v6, vcc
	v_cndmask_b32_e32 v5, v5, v7, vcc
	v_add_u32_e32 v6, 1, v2
	v_cmp_ge_u32_e32 vcc, v5, v3
	s_nop 1
	v_cndmask_b32_e32 v2, v2, v6, vcc
	v_mul_lo_u32 v5, v3, v2
	v_add_u32_e32 v3, v5, v3
	v_cmp_ne_u32_e32 vcc, v4, v3
	s_and_saveexec_b64 s[2:3], vcc
	s_xor_b64 s[34:35], exec, s[2:3]
	s_cbranch_execz .LBB0_309
	s_waitcnt lgkmcnt(0)
	buffer_inv sc1
	v_readlane_b32 s98, v247, 3
	v_readlane_b32 s99, v247, 4
	s_nop 4
	global_load_dword v0, v1, s[98:99] sc1
	s_waitcnt vmcnt(0)
	v_cmp_eq_u32_e32 vcc, v0, v2
	s_and_saveexec_b64 s[40:41], vcc
	s_cbranch_execz .LBB0_308
	s_mov_b32 s2, 1
	s_mov_b64 s[42:43], 0
	s_branch .LBB0_299

; __device__ __forceinline__ unsigned xb_ld(unsigned* p)              { return __hip_atomic_load(p, __ATOMIC_RELAXED, __HIP_MEMORY_SCOPE_AGENT); }
; __device__ __forceinline__ unsigned xb_add(unsigned* p, unsigned v) { return __hip_atomic_fetch_add(p, v, __ATOMIC_RELAXED, __HIP_MEMORY_SCOPE_AGENT); }
; #define XB_SPIN(cond, bar) do { unsigned _sp = 0; while (cond) { __builtin_amdgcn_s_sleep(1); \
;     if ((++_sp & 255u) == 0u) { if (xb_ld(&(bar)[XB_TMO])) break; if (_sp > XB_SPIN_CAP) { atomicAdd(&(bar)[XB_TMO], 1u); break; } } } } while (0)
; __device__ __forceinline__ void xcd_barrier(const XcdBarrier& b) {
;     ...
;         if (old + 1u == (gen + 1u) * nloc) {
;             __builtin_amdgcn_fence(__ATOMIC_RELEASE, "agent");
;             asm volatile("s_waitcnt vmcnt(0)" ::: "memory");
;             const unsigned og = xb_add(&bar[XB_TOP], 1u);
;     ...
;         } else {
;             XB_SPIN(xb_ld(&bar[XB_XGEN(b.x)]) == gen, bar);
;             __builtin_amdgcn_fence(__ATOMIC_ACQUIRE, "agent");
;             asm volatile("s_waitcnt vmcnt(0)" ::: "memory");
.LBB0_308:
	s_or_b64 exec, exec, s[40:41]
	s_waitcnt vmcnt(0)
	s_waitcnt vmcnt(0)
.LBB0_309:
	s_andn2_saveexec_b64 s[34:35], s[34:35]
	s_cbranch_execz .LBB0_327
	s_mov_b64 s[40:41], exec
	buffer_wbl2 sc1
	s_waitcnt lgkmcnt(0)
	s_waitcnt vmcnt(0)
	v_mbcnt_lo_u32_b32 v2, s40, 0
	v_mbcnt_hi_u32_b32 v2, s41, v2
	v_cmp_eq_u32_e32 vcc, 0, v2
	s_and_saveexec_b64 s[42:43], vcc
	s_cbranch_execz .LBB0_312
	s_bcnt1_i32_b64 s2, s[40:41]
	v_mov_b32_e32 v3, s2
	v_readlane_b32 s2, v247, 1
	v_readlane_b32 s3, v247, 2
	s_nop 4
	global_atomic_add v3, v1, v3, s[2:3] sc0
	buffer_inv sc1

; __device__ __forceinline__ unsigned xb_ld(unsigned* p)              { return __hip_atomic_load(p, __ATOMIC_RELAXED, __HIP_MEMORY_SCOPE_AGENT); }
; __device__ __forceinline__ unsigned xb_add(unsigned* p, unsigned v) { return __hip_atomic_fetch_add(p, v, __ATOMIC_RELAXED, __HIP_MEMORY_SCOPE_AGENT); }
; #define XB_SPIN(cond, bar) do { unsigned _sp = 0; while (cond) { __builtin_amdgcn_s_sleep(1); \
;     if ((++_sp & 255u) == 0u) { if (xb_ld(&(bar)[XB_TMO])) break; if (_sp > XB_SPIN_CAP) { atomicAdd(&(bar)[XB_TMO], 1u); break; } } } } while (0)
; __device__ __forceinline__ void xcd_barrier(const XcdBarrier& b) {
;     ...
;         const unsigned old = xb_add(&bar[XB_XSUB(b.x)], 1u);
;         const unsigned gen = old / nloc;
;         if (old + 1u == (gen + 1u) * nloc) {
;             __builtin_amdgcn_fence(__ATOMIC_RELEASE, "agent");
;             asm volatile("s_waitcnt vmcnt(0)" ::: "memory");
;             const unsigned og = xb_add(&bar[XB_TOP], 1u);
;             const unsigned tg = og / nx;
;             if (og + 1u == (tg + 1u) * nx) xb_add(&bar[XB_TOPGEN], 1u);
;             else XB_SPIN(xb_ld(&bar[XB_TOPGEN]) == tg, bar);
;             __builtin_amdgcn_fence(__ATOMIC_ACQUIRE, "agent");
;             xb_add(&bar[XB_XGEN(b.x)], 1u);
;             asm volatile("s_waitcnt vmcnt(0)" ::: "memory");
;         } else {
;             XB_SPIN(xb_ld(&bar[XB_XGEN(b.x)]) == gen, bar);
;             __builtin_amdgcn_fence(__ATOMIC_ACQUIRE, "agent");
.LBB0_568:
	global_atomic_add v4, v[190:191], v220, off sc0
	v_cvt_f32_u32_e32 v0, v3
	v_sub_u32_e32 v5, 0, v3
	v_rcp_iflag_f32_e32 v0, v0
	s_nop 0
	v_mul_f32_e32 v0, 0x4f7ffffe, v0
	v_cvt_u32_f32_e32 v0, v0
	v_mul_lo_u32 v5, v5, v0
	v_mul_hi_u32 v5, v0, v5
	v_add_u32_e32 v0, v0, v5
	s_waitcnt vmcnt(0)
	v_mul_hi_u32 v0, v4, v0
	v_mul_lo_u32 v5, v0, v3
	v_sub_u32_e32 v5, v4, v5
	v_add_u32_e32 v6, 1, v0
	v_cmp_ge_u32_e32 vcc, v5, v3
	v_add_u32_e32 v4, 1, v4
	s_nop 0
	v_cndmask_b32_e32 v0, v0, v6, vcc
	v_sub_u32_e32 v6, v5, v3
	v_cndmask_b32_e32 v5, v5, v6, vcc
	v_add_u32_e32 v6, 1, v0
	v_cmp_ge_u32_e32 vcc, v5, v3
	s_nop 1
	v_cndmask_b32_e32 v0, v0, v6, vcc
	v_mul_lo_u32 v5, v3, v0
	v_add_u32_e32 v3, v5, v3
	v_cmp_ne_u32_e32 vcc, v4, v3
	s_and_saveexec_b64 s[2:3], vcc
	s_xor_b64 s[34:35], exec, s[2:3]
	s_cbranch_execz .LBB0_582
	s_waitcnt lgkmcnt(0)
	buffer_inv sc1
	v_readlane_b32 s98, v247, 3
	v_readlane_b32 s99, v247, 4
	s_nop 4
	global_load_dword v2, v1, s[98:99] sc1
	s_waitcnt vmcnt(0)
	v_cmp_eq_u32_e32 vcc, v2, v0
	s_and_saveexec_b64 s[40:41], vcc
	s_cbranch_execz .LBB0_581
	s_mov_b32 s2, 1
	s_mov_b64 s[42:43], 0
	s_branch .LBB0_572

; __device__ __forceinline__ unsigned xb_add(unsigned* p, unsigned v) { return __hip_atomic_fetch_add(p, v, __ATOMIC_RELAXED, __HIP_MEMORY_SCOPE_AGENT); }
; __device__ __forceinline__ void xcd_barrier(const XcdBarrier& b) {
;     ...
;         if (old + 1u == (gen + 1u) * nloc) {
;             __builtin_amdgcn_fence(__ATOMIC_RELEASE, "agent");
;             asm volatile("s_waitcnt vmcnt(0)" ::: "memory");
;             const unsigned og = xb_add(&bar[XB_TOP], 1u);
.LBB0_582:
	s_andn2_saveexec_b64 s[34:35], s[34:35]
	s_cbranch_execz .LBB0_600
	s_mov_b64 s[40:41], exec
	buffer_wbl2 sc1
	s_waitcnt lgkmcnt(0)
	s_waitcnt vmcnt(0)
	v_mbcnt_lo_u32_b32 v0, s40, 0
	v_mbcnt_hi_u32_b32 v0, s41, v0
	v_cmp_eq_u32_e32 vcc, 0, v0
	s_and_saveexec_b64 s[42:43], vcc
	s_cbranch_execz .LBB0_585
	s_bcnt1_i32_b64 s2, s[40:41]
	v_mov_b32_e32 v3, s2
	v_readlane_b32 s2, v247, 1
	v_readlane_b32 s3, v247, 2
	s_nop 4
	global_atomic_add v3, v1, v3, s[2:3] sc0
	buffer_inv sc1

; __device__ __forceinline__ unsigned xb_ld(unsigned* p)              { return __hip_atomic_load(p, __ATOMIC_RELAXED, __HIP_MEMORY_SCOPE_AGENT); }
; __device__ __forceinline__ unsigned xb_add(unsigned* p, unsigned v) { return __hip_atomic_fetch_add(p, v, __ATOMIC_RELAXED, __HIP_MEMORY_SCOPE_AGENT); }
; #define XB_SPIN(cond, bar) do { unsigned _sp = 0; while (cond) { __builtin_amdgcn_s_sleep(1); \
;     if ((++_sp & 255u) == 0u) { if (xb_ld(&(bar)[XB_TMO])) break; if (_sp > XB_SPIN_CAP) { atomicAdd(&(bar)[XB_TMO], 1u); break; } } } } while (0)
; __device__ __forceinline__ void xcd_barrier(const XcdBarrier& b) {
;     ...
;         const unsigned old = xb_add(&bar[XB_XSUB(b.x)], 1u);
;         const unsigned gen = old / nloc;
;         if (old + 1u == (gen + 1u) * nloc) {
;             __builtin_amdgcn_fence(__ATOMIC_RELEASE, "agent");
;             asm volatile("s_waitcnt vmcnt(0)" ::: "memory");
;             const unsigned og = xb_add(&bar[XB_TOP], 1u);
;             const unsigned tg = og / nx;
;             if (og + 1u == (tg + 1u) * nx) xb_add(&bar[XB_TOPGEN], 1u);
;             else XB_SPIN(xb_ld(&bar[XB_TOPGEN]) == tg, bar);
;             __builtin_amdgcn_fence(__ATOMIC_ACQUIRE, "agent");
;             xb_add(&bar[XB_XGEN(b.x)], 1u);
;             asm volatile("s_waitcnt vmcnt(0)" ::: "memory");
;         } else {
;             XB_SPIN(xb_ld(&bar[XB_XGEN(b.x)]) == gen, bar);
;             __builtin_amdgcn_fence(__ATOMIC_ACQUIRE, "agent");
.LBB0_632:
	global_atomic_add v4, v[190:191], v220, off sc0
	v_cvt_f32_u32_e32 v0, v3
	v_sub_u32_e32 v5, 0, v3
	v_rcp_iflag_f32_e32 v0, v0
	s_nop 0
	v_mul_f32_e32 v0, 0x4f7ffffe, v0
	v_cvt_u32_f32_e32 v0, v0
	v_mul_lo_u32 v5, v5, v0
	v_mul_hi_u32 v5, v0, v5
	v_add_u32_e32 v0, v0, v5
	s_waitcnt vmcnt(0)
	v_mul_hi_u32 v0, v4, v0
	v_mul_lo_u32 v5, v0, v3
	v_sub_u32_e32 v5, v4, v5
	v_add_u32_e32 v6, 1, v0
	v_cmp_ge_u32_e32 vcc, v5, v3
	v_add_u32_e32 v4, 1, v4
	s_nop 0
	v_cndmask_b32_e32 v0, v0, v6, vcc
	v_sub_u32_e32 v6, v5, v3
	v_cndmask_b32_e32 v5, v5, v6, vcc
	v_add_u32_e32 v6, 1, v0
	v_cmp_ge_u32_e32 vcc, v5, v3
	s_nop 1
	v_cndmask_b32_e32 v0, v0, v6, vcc
	v_mul_lo_u32 v5, v3, v0
	v_add_u32_e32 v3, v5, v3
	v_cmp_ne_u32_e32 vcc, v4, v3
	s_and_saveexec_b64 s[2:3], vcc
	s_xor_b64 s[16:17], exec, s[2:3]
	s_cbranch_execz .LBB0_646
	s_waitcnt lgkmcnt(0)
	buffer_inv sc1
	v_readlane_b32 s98, v247, 3
	v_readlane_b32 s99, v247, 4
	s_nop 4
	global_load_dword v2, v1, s[98:99] sc1
	s_waitcnt vmcnt(0)
	v_cmp_eq_u32_e32 vcc, v2, v0
	s_and_saveexec_b64 s[34:35], vcc
	s_cbranch_execz .LBB0_645
	s_mov_b32 s2, 1
	s_mov_b64 s[40:41], 0
	s_branch .LBB0_636

; __device__ __forceinline__ unsigned xb_add(unsigned* p, unsigned v) { return __hip_atomic_fetch_add(p, v, __ATOMIC_RELAXED, __HIP_MEMORY_SCOPE_AGENT); }
; __device__ __forceinline__ void xcd_barrier(const XcdBarrier& b) {
;     ...
;         if (old + 1u == (gen + 1u) * nloc) {
;             __builtin_amdgcn_fence(__ATOMIC_RELEASE, "agent");
;             asm volatile("s_waitcnt vmcnt(0)" ::: "memory");
;             const unsigned og = xb_add(&bar[XB_TOP], 1u);
.LBB0_646:
	s_andn2_saveexec_b64 s[16:17], s[16:17]
	s_cbranch_execz .LBB0_664
	s_mov_b64 s[34:35], exec
	buffer_wbl2 sc1
	s_waitcnt lgkmcnt(0)
	s_waitcnt vmcnt(0)
	v_mbcnt_lo_u32_b32 v0, s34, 0
	v_mbcnt_hi_u32_b32 v0, s35, v0
	v_cmp_eq_u32_e32 vcc, 0, v0
	s_and_saveexec_b64 s[40:41], vcc
	s_cbranch_execz .LBB0_649
	s_bcnt1_i32_b64 s2, s[34:35]
	v_mov_b32_e32 v3, s2
	v_readlane_b32 s2, v247, 1
	v_readlane_b32 s3, v247, 2
	s_nop 4
	global_atomic_add v3, v1, v3, s[2:3] sc0
	buffer_inv sc1

; __device__ __forceinline__ unsigned xb_add(unsigned* p, unsigned v) { return __hip_atomic_fetch_add(p, v, __ATOMIC_RELAXED, __HIP_MEMORY_SCOPE_AGENT); }
; __device__ __forceinline__ void xcd_barrier(const XcdBarrier& b) {
;     ...
;         if (old + 1u == (gen + 1u) * nloc) {
;             __builtin_amdgcn_fence(__ATOMIC_RELEASE, "agent");
;             asm volatile("s_waitcnt vmcnt(0)" ::: "memory");
;             const unsigned og = xb_add(&bar[XB_TOP], 1u);
.LBB0_716:
	s_mov_b64 s[16:17], exec
	buffer_wbl2 sc1
	s_waitcnt lgkmcnt(0)
	s_waitcnt vmcnt(0)
	v_mbcnt_lo_u32_b32 v0, s16, 0
	v_mbcnt_hi_u32_b32 v0, s17, v0
	v_cmp_eq_u32_e32 vcc, 0, v0
	s_and_saveexec_b64 s[34:35], vcc
	s_cbranch_execz .LBB0_718
	s_bcnt1_i32_b64 s2, s[16:17]
	v_mov_b32_e32 v3, s2
	v_readlane_b32 s2, v247, 1
	v_readlane_b32 s3, v247, 2
	s_nop 4
	global_atomic_add v3, v1, v3, s[2:3] sc0
	buffer_inv sc1
